# v021 + softmax row-max exchange by v_permlane32_swap in all three attention DMA loops (6 sites)
# speedup vs baseline: 1.0094x; 1.0013x over previous
; #define LAS __attribute__((address_space(3)))
; __device__ __forceinline__ int crow(int r, int hi) { return (r & 3) + 8 * (r >> 2) + 4 * hi; }
;     ...
;     auto QK = [&](const LAS unsigned char* sbase, f32x16& s0, f32x16& s1) {
;         const LAS unsigned char* kb = sbase + r32 * KSTR; const int kc0 = (koff >> 3) + hi;
; #pragma unroll
;         for (int r = 0; r < 16; ++r) { s0[r] = 0.f; s1[r] = 0.f; }
; #pragma unroll
;         for (int kh = 0; kh < NKS; kh += 4) {
;             bf16x8 ka[4][2];
; #pragma unroll
;             for (int ks = 0; ks < 4; ++ks) { const int ko = ((kc0 + 2 * (kh + ks)) ^ ksw) << 4; ka[ks][0] = *(const LAS bf16x8*)(kb + ko); ka[ks][1] = *(const LAS bf16x8*)(kb + 32 * KSTR + ko); }
;             __builtin_amdgcn_s_setprio(1);
; #pragma unroll
;             for (int ks = 0; ks < 4; ++ks) { s0 = __builtin_amdgcn_mfma_f32_32x32x16_bf16(ka[ks][0], qf[kh + ks], s0, 0, 0, 0); s1 = __builtin_amdgcn_mfma_f32_32x32x16_bf16(ka[ks][1], qf[kh + ks], s1, 0, 0, 0); }
;             __builtin_amdgcn_s_setprio(0);
;         }
;     };
;     auto SM = [&](unsigned w0, unsigned w1, f32x16& s0, f32x16& s1, bf16x8 (&pb)[2][2]) {
;         if (LAYER == 1) {
; #pragma unroll
;             for (int r = 0; r < 16; ++r) { const int kv = crow(r, hi); if (!((w0 >> kv) & 1u)) s0[r] = -1e30f; if (!((w1 >> kv) & 1u)) s1[r] = -1e30f; } }
;         float mx = fmaxf(s0[0], s1[0]);
; #pragma unroll
;         for (int r = 1; r < 16; ++r) mx = fmaxf(mx, fmaxf(s0[r], s1[r]));
;         mx = fmaxf(mx, __shfl_xor(mx, 32));
;     ...
;             if (LAYER == 1) { const v2u ma = *(const LAS v2u*)(sa + 2 * STAGEB + (32 * sb + r32) * 8), mb = *(const LAS v2u*)(sa + 2 * STAGEB + MSKB + (32 * sb + r32) * 8); wa0 = ma.x; wa1 = ma.y; wb0 = mb.x; wb1 = mb.y; }
;             if (wka) QK(sa, a0, a1);
.LBB0_2110:
	s_bitcmp1_b32 s4, 0
	s_cselect_b32 s0, 0x10400, 0
	s_add_i32 s0, s0, 0
	v_add_u32_e32 v82, s0, v172
	v_add_u32_e32 v83, 0x10200, v82
	s_waitcnt lgkmcnt(0)
	ds_read_b64 v[156:157], v83
	v_add_u32_e32 v83, s0, v173
	v_add_u32_e32 v84, s0, v171
	s_cmp_gt_i32 s85, s90
	v_add_u32_e32 v214, v83, v174
	v_add_u32_e32 v213, v83, v175
	v_add_u32_e32 v212, v83, v176
	v_add_u32_e32 v211, v83, v177
	v_add_u32_e32 v210, v83, v178
	v_add_u32_e32 v209, v83, v179
	v_add_u32_e32 v208, v83, v180
	v_add_u32_e32 v207, v83, v181
	v_add_u32_e32 v155, v84, v161
	v_add_u32_e32 v199, v84, v162
	v_add_u32_e32 v200, v84, v163
	v_add_u32_e32 v201, v84, v166
	v_add_u32_e32 v202, v84, v167
	v_add_u32_e32 v203, v84, v168
	v_add_u32_e32 v204, v84, v169
	v_add_u32_e32 v205, v84, v170
	s_cbranch_scc1 .LBB0_2114
	v_add_u32_e32 v82, 0x10000, v82
	ds_read_b64 v[240:241], v82
	ds_read_b128 v[82:85], v214
	ds_read_b128 v[98:101], v214 offset:8192
	ds_read_b128 v[102:105], v213
	ds_read_b128 v[134:137], v213 offset:8192
	ds_read_b128 v[106:109], v212
	ds_read_b128 v[138:141], v212 offset:8192
	ds_read_b128 v[110:113], v211
	ds_read_b128 v[216:219], v211 offset:8192
	s_setprio 1
	s_waitcnt lgkmcnt(0)
	v_mfma_f32_32x32x16_bf16 v[82:97], v[82:85], v[4:7], 0
	v_mfma_f32_32x32x16_bf16 v[82:97], v[102:105], v[8:11], v[82:97]
	v_mfma_f32_32x32x16_bf16 v[82:97], v[106:109], v[12:15], v[82:97]
	v_mfma_f32_32x32x16_bf16 v[82:97], v[110:113], v[114:117], v[82:97]
	s_setprio 0
	ds_read_b128 v[102:105], v210
	ds_read_b128 v[224:227], v210 offset:8192
	ds_read_b128 v[106:109], v209
	ds_read_b128 v[228:231], v209 offset:8192
	ds_read_b128 v[110:113], v208
	ds_read_b128 v[232:235], v208 offset:8192
	ds_read_b128 v[220:223], v207
	ds_read_b128 v[236:239], v207 offset:8192
	s_setprio 1
	s_waitcnt lgkmcnt(0)
	v_mfma_f32_32x32x16_bf16 v[82:97], v[102:105], v[118:121], v[82:97]
	v_mfma_f32_32x32x16_bf16 v[82:97], v[106:109], v[122:125], v[82:97]
	v_mfma_f32_32x32x16_bf16 v[82:97], v[110:113], v[126:129], v[82:97]
	v_mfma_f32_32x32x16_bf16 v[82:97], v[220:223], v[130:133], v[82:97]
	s_setprio 0
	v_mfma_f32_32x32x16_bf16 v[98:113], v[98:101], v[4:7], 0
	v_and_b32_e32 v215, v240, v182
	v_cmp_eq_u32_e64 s[20:21], 0, v215
	v_and_b32_e32 v221, v240, v183
	v_cmp_eq_u32_e64 s[10:11], 0, v221
	s_nop 5
	v_cndmask_b32_e64 v220, v82, v158, s[20:21]
	v_and_b32_e32 v82, v241, v183
	v_cmp_eq_u32_e64 s[66:67], 0, v82
	v_mfma_f32_32x32x16_bf16 v[98:113], v[134:137], v[8:11], v[98:113]
	v_and_b32_e32 v82, v240, v191
	v_cmp_eq_u32_e64 s[50:51], 0, v82
	v_and_b32_e32 v82, v241, v191
	v_cmp_eq_u32_e64 s[52:53], 0, v82
	v_and_b32_e32 v82, v240, v193
	v_cmp_eq_u32_e64 s[46:47], 0, v82
	v_and_b32_e32 v82, v241, v193
	v_mfma_f32_32x32x16_bf16 v[98:113], v[138:141], v[12:15], v[98:113]
	v_cmp_eq_u32_e64 s[48:49], 0, v82
	v_and_b32_e32 v82, v240, v194
	v_cmp_eq_u32_e64 s[40:41], 0, v82
	v_and_b32_e32 v82, v241, v194
	v_cmp_eq_u32_e64 s[42:43], 0, v82
	v_and_b32_e32 v82, v240, v195
	v_cmp_eq_u32_e64 s[36:37], 0, v82
	v_mfma_f32_32x32x16_bf16 v[98:113], v[216:219], v[114:117], v[98:113]
	v_and_b32_e32 v82, v241, v195
	v_cmp_eq_u32_e64 s[38:39], 0, v82
	v_and_b32_e32 v82, v240, v196
	v_cmp_eq_u32_e64 s[30:31], 0, v82
	v_and_b32_e32 v82, v241, v196
	v_cmp_eq_u32_e64 s[34:35], 0, v82
	v_and_b32_e32 v82, v240, v197
	v_mfma_f32_32x32x16_bf16 v[98:113], v[224:227], v[118:121], v[98:113]
	v_cndmask_b32_e64 v218, v83, v158, s[10:11]
	v_and_b32_e32 v83, v240, v184
	v_cmp_eq_u32_e64 s[26:27], 0, v82
	v_and_b32_e32 v82, v241, v197
	v_and_b32_e32 v242, v241, v184
	v_cmp_eq_u32_e64 s[18:19], 0, v83
	v_cmp_eq_u32_e64 s[28:29], 0, v82
	v_mfma_f32_32x32x16_bf16 v[98:113], v[228:231], v[122:125], v[98:113]
	v_and_b32_e32 v82, v240, v198
	v_and_b32_e32 v215, v240, v185
	v_cndmask_b32_e64 v222, v84, v158, s[18:19]
	v_and_b32_e32 v83, v241, v185
	v_and_b32_e32 v84, v240, v186
	v_cmp_eq_u32_e64 s[64:65], 0, v242
	v_cmp_eq_u32_e64 s[22:23], 0, v82
	v_mfma_f32_32x32x16_bf16 v[98:113], v[232:235], v[126:129], v[98:113]
	v_and_b32_e32 v82, v241, v198
	v_and_b32_e32 v223, v241, v182
	v_cmp_eq_u32_e64 s[8:9], 0, v215
	v_cmp_eq_u32_e64 s[16:17], 0, v84
	v_and_b32_e32 v84, v241, v187
	v_cmp_eq_u32_e64 s[62:63], 0, v83
	v_cmp_eq_u32_e64 s[24:25], 0, v82
	v_mfma_f32_32x32x16_bf16 v[98:113], v[236:239], v[130:133], v[98:113]
	v_max_f32_e32 v83, v218, v218
	v_cndmask_b32_e64 v217, v85, v158, s[8:9]
	v_and_b32_e32 v85, v241, v186
	v_cmp_eq_u32_e64 s[68:69], 0, v223
	v_cmp_eq_u32_e64 s[58:59], 0, v84
	v_max_f32_e32 v84, v222, v222
	v_and_b32_e32 v215, v240, v187
	s_nop 4
	v_cndmask_b32_e64 v230, v99, v158, s[66:67]
	v_cndmask_b32_e64 v229, v100, v158, s[64:65]
	v_max_f32_e32 v82, v230, v230
	v_cndmask_b32_e64 v228, v101, v158, s[62:63]
	v_max_f32_e32 v82, v83, v82
	v_max_f32_e32 v83, v229, v229
	v_cndmask_b32_e64 v231, v98, v158, s[68:69]
	v_cmp_eq_u32_e64 s[60:61], 0, v85
	v_max_f32_e32 v83, v84, v83
	v_max_f32_e32 v84, v228, v228
	v_max_f32_e32 v85, v217, v217
	v_cndmask_b32_e64 v221, v86, v158, s[16:17]
	v_cmp_eq_u32_e64 s[4:5], 0, v215
	v_cndmask_b32_e64 v227, v102, v158, s[60:61]
	v_max3_f32 v82, v220, v231, v82
	v_max_f32_e32 v84, v85, v84
	v_cndmask_b32_e64 v215, v87, v158, s[4:5]
	v_and_b32_e32 v86, v240, v188
	v_and_b32_e32 v87, v241, v188
	v_cndmask_b32_e64 v226, v103, v158, s[58:59]
	v_max3_f32 v82, v82, v83, v84
	v_max_f32_e32 v83, v227, v227
	v_max_f32_e32 v84, v221, v221
	v_and_b32_e32 v216, v240, v189
	v_cmp_eq_u32_e64 s[14:15], 0, v86
	v_and_b32_e32 v86, v241, v189
	v_cmp_eq_u32_e64 s[56:57], 0, v87
	v_max_f32_e32 v83, v84, v83
	v_max_f32_e32 v84, v226, v226
	v_max_f32_e32 v85, v215, v215
	v_cndmask_b32_e64 v219, v88, v158, s[14:15]
; __device__ __forceinline__ int crow(int r, int hi) { return (r & 3) + 8 * (r >> 2) + 4 * hi; }
;     ...
;             for (int r = 0; r < 16; ++r) { const int kv = crow(r, hi); if (!((w0 >> kv) & 1u)) s0[r] = -1e30f; if (!((w1 >> kv) & 1u)) s1[r] = -1e30f; } }
;         float mx = fmaxf(s0[0], s1[0]);
; #pragma unroll
;         for (int r = 1; r < 16; ++r) mx = fmaxf(mx, fmaxf(s0[r], s1[r]));
;         mx = fmaxf(mx, __shfl_xor(mx, 32));
;         const bool need = mx > mrun + 8.f;
;         if (__any(need)) { const float mnew = need ? mx : mrun, alpha = __builtin_amdgcn_exp2f(mrun - mnew); mrun = mnew; lrun *= alpha;
; #pragma unroll
;             for (int d = 0; d < 4; ++d)
; #pragma unroll
;                 for (int r = 0; r < 16; ++r) o[d][r] *= alpha; }
	v_cmp_eq_u32_e64 s[6:7], 0, v216
	v_cndmask_b32_e64 v225, v104, v158, s[56:57]
	v_cmp_eq_u32_e64 s[54:55], 0, v86
	v_max_f32_e32 v84, v85, v84
	v_cndmask_b32_e64 v216, v89, v158, s[6:7]
	v_and_b32_e32 v88, v240, v190
	v_and_b32_e32 v89, v241, v190
	v_cndmask_b32_e64 v223, v105, v158, s[54:55]
	v_max3_f32 v82, v82, v83, v84
	v_max_f32_e32 v83, v225, v225
	v_max_f32_e32 v84, v219, v219
	v_cmp_eq_u32_e64 s[12:13], 0, v88
	v_cmp_eq_u32_e64 s[44:45], 0, v89
	v_max_f32_e32 v83, v84, v83
	v_max_f32_e32 v84, v223, v223
	v_max_f32_e32 v85, v216, v216
	v_cndmask_b32_e64 v90, v90, v158, s[12:13]
	v_cndmask_b32_e64 v224, v106, v158, s[44:45]
	v_max_f32_e32 v84, v85, v84
	v_cndmask_b32_e64 v105, v91, v158, s[50:51]
	v_cndmask_b32_e64 v106, v107, v158, s[52:53]
	v_max3_f32 v82, v82, v83, v84
	v_max_f32_e32 v83, v224, v224
	v_max_f32_e32 v84, v90, v90
	v_max_f32_e32 v83, v84, v83
	v_max_f32_e32 v84, v106, v106
	v_max_f32_e32 v85, v105, v105
	v_cndmask_b32_e64 v103, v92, v158, s[46:47]
	v_cndmask_b32_e64 v104, v108, v158, s[48:49]
	v_max_f32_e32 v84, v85, v84
	v_cndmask_b32_e64 v101, v93, v158, s[40:41]
	v_cndmask_b32_e64 v102, v109, v158, s[42:43]
	v_max3_f32 v82, v82, v83, v84
	v_max_f32_e32 v83, v104, v104
	v_max_f32_e32 v84, v103, v103
	v_max_f32_e32 v83, v84, v83
	v_max_f32_e32 v84, v102, v102
	v_max_f32_e32 v85, v101, v101
	v_cndmask_b32_e64 v99, v94, v158, s[36:37]
	v_cndmask_b32_e64 v100, v110, v158, s[38:39]
	v_max_f32_e32 v84, v85, v84
	v_cndmask_b32_e64 v95, v95, v158, s[30:31]
	v_cndmask_b32_e64 v98, v111, v158, s[34:35]
	v_max3_f32 v82, v82, v83, v84
	v_max_f32_e32 v83, v100, v100
	v_max_f32_e32 v84, v99, v99
	v_max_f32_e32 v83, v84, v83
	v_max_f32_e32 v84, v98, v98
	v_max_f32_e32 v85, v95, v95
	v_cndmask_b32_e64 v93, v96, v158, s[26:27]
	v_cndmask_b32_e64 v94, v112, v158, s[28:29]
	v_max_f32_e32 v84, v85, v84
	v_cndmask_b32_e64 v91, v97, v158, s[22:23]
	v_cndmask_b32_e64 v92, v113, v158, s[24:25]
	v_max3_f32 v82, v82, v83, v84
	v_max_f32_e32 v83, v94, v94
	v_max_f32_e32 v84, v93, v93
	v_max_f32_e32 v83, v84, v83
	v_max_f32_e32 v84, v92, v92
	v_max_f32_e32 v85, v91, v91
	v_max_f32_e32 v84, v85, v84
	v_max3_f32 v96, v82, v83, v84
	s_waitcnt vmcnt(0)
	ds_read_b64_tr_b16 v[138:139], v155 offset:16384
	ds_read_b64_tr_b16 v[140:141], v199 offset:18432
	ds_read_b64_tr_b16 v[134:135], v200 offset:16384
	ds_read_b64_tr_b16 v[136:137], v201 offset:18432
	v_mov_b32_e32 v246, v96
	v_mov_b32_e32 v247, v96
	ds_read_b64_tr_b16 v[86:87], v202 offset:16384
	ds_read_b64_tr_b16 v[88:89], v203 offset:18432
	ds_read_b64_tr_b16 v[82:83], v204 offset:16384
	ds_read_b64_tr_b16 v[84:85], v205 offset:18432
	v_permlane32_swap_b32_e32 v246, v247
	v_max3_f32 v96, v96, v246, v247
	v_add_f32_e32 v97, 0x41000000, v206
	v_cmp_gt_f32_e32 vcc, v96, v97
	s_cbranch_vccz .LBB0_2113
	s_nop 0
	v_cndmask_b32_e32 v97, v206, v96, vcc
	v_sub_f32_e32 v96, v206, v97
	v_exp_f32_e32 v96, v96
	v_mov_b32_e32 v206, v97
	v_mul_f32_e32 v192, v192, v96
	v_pk_mul_f32 v[80:81], v[80:81], v[96:97] op_sel_hi:[1,0]
	v_pk_mul_f32 v[78:79], v[78:79], v[96:97] op_sel_hi:[1,0]
	v_pk_mul_f32 v[76:77], v[76:77], v[96:97] op_sel_hi:[1,0]
	v_pk_mul_f32 v[74:75], v[74:75], v[96:97] op_sel_hi:[1,0]
	v_pk_mul_f32 v[72:73], v[72:73], v[96:97] op_sel_hi:[1,0]
	v_pk_mul_f32 v[70:71], v[70:71], v[96:97] op_sel_hi:[1,0]
	v_pk_mul_f32 v[68:69], v[68:69], v[96:97] op_sel_hi:[1,0]
	v_pk_mul_f32 v[66:67], v[66:67], v[96:97] op_sel_hi:[1,0]
	v_pk_mul_f32 v[64:65], v[64:65], v[96:97] op_sel_hi:[1,0]
	v_pk_mul_f32 v[62:63], v[62:63], v[96:97] op_sel_hi:[1,0]
	v_pk_mul_f32 v[60:61], v[60:61], v[96:97] op_sel_hi:[1,0]
	v_pk_mul_f32 v[58:59], v[58:59], v[96:97] op_sel_hi:[1,0]
	v_pk_mul_f32 v[56:57], v[56:57], v[96:97] op_sel_hi:[1,0]
	v_pk_mul_f32 v[54:55], v[54:55], v[96:97] op_sel_hi:[1,0]
	v_pk_mul_f32 v[52:53], v[52:53], v[96:97] op_sel_hi:[1,0]
	v_pk_mul_f32 v[50:51], v[50:51], v[96:97] op_sel_hi:[1,0]
	v_pk_mul_f32 v[48:49], v[48:49], v[96:97] op_sel_hi:[1,0]
	v_pk_mul_f32 v[46:47], v[46:47], v[96:97] op_sel_hi:[1,0]
	v_pk_mul_f32 v[44:45], v[44:45], v[96:97] op_sel_hi:[1,0]
	v_pk_mul_f32 v[42:43], v[42:43], v[96:97] op_sel_hi:[1,0]
	v_pk_mul_f32 v[40:41], v[40:41], v[96:97] op_sel_hi:[1,0]
	v_pk_mul_f32 v[38:39], v[38:39], v[96:97] op_sel_hi:[1,0]
	v_pk_mul_f32 v[36:37], v[36:37], v[96:97] op_sel_hi:[1,0]
	v_pk_mul_f32 v[34:35], v[34:35], v[96:97] op_sel_hi:[1,0]
	v_pk_mul_f32 v[32:33], v[32:33], v[96:97] op_sel_hi:[1,0]
	v_pk_mul_f32 v[30:31], v[30:31], v[96:97] op_sel_hi:[1,0]
	v_pk_mul_f32 v[28:29], v[28:29], v[96:97] op_sel_hi:[1,0]
	v_pk_mul_f32 v[26:27], v[26:27], v[96:97] op_sel_hi:[1,0]
	v_pk_mul_f32 v[24:25], v[24:25], v[96:97] op_sel_hi:[1,0]
	v_pk_mul_f32 v[22:23], v[22:23], v[96:97] op_sel_hi:[1,0]
	v_pk_mul_f32 v[20:21], v[20:21], v[96:97] op_sel_hi:[1,0]
	v_pk_mul_f32 v[18:19], v[18:19], v[96:97] op_sel_hi:[1,0]
; __device__ __forceinline__ unsigned cvtpk(float lo, float hi) { typedef __bf16 b2 __attribute__((ext_vector_type(2))); f32x2 v = {lo, hi}; b2 b = __builtin_convertvector(v, b2); return __builtin_bit_cast(unsigned, b); }
; __device__ __forceinline__ int crow(int r, int hi) { return (r & 3) + 8 * (r >> 2) + 4 * hi; }
; #define ATT_VREAD(dst, q_) do { const LAS char* vp_ = (const LAS char*)vb + (((q_) >> 1) * 32 + 16 * ((q_) & 1)) * VSTR; \
;         _Pragma("unroll") for (int d_ = 0; d_ < 4; ++d_) { dst[d_][0] = vtr(vp_ + voff[d_][0]); dst[d_][1] = vtr(vp_ + 8 * VSTR + voff[d_][1]); } } while (0)
; #define ATT_PV(src, pb_, q_) do { _Pragma("unroll") for (int d_ = 0; d_ < 4; ++d_) { const s16x4 lo_ = src[d_][0], hh_ = src[d_][1]; \
;         const bf16x8 vf_ = (bf16x8){lo_[0], lo_[1], lo_[2], lo_[3], hh_[0], hh_[1], hh_[2], hh_[3]}; o[d_] = __builtin_amdgcn_mfma_f32_32x32x16_bf16(vf_, pb_[(q_) >> 1][(q_) & 1], o[d_], 0, 0, 0); } } while (0)
;     ...
;         float rsa[4] = {0.f, 0.f, 0.f, 0.f};
; #pragma unroll
;         for (int r = 0; r < 16; ++r) { float p0 = __builtin_amdgcn_exp2f(s0[r] - mrun), p1 = __builtin_amdgcn_exp2f(s1[r] - mrun);
;             if (LAYER == 1) { const int kv = crow(r, hi); p0 = ((w0 >> kv) & 1u) ? p0 : 0.f; p1 = ((w1 >> kv) & 1u) ? p1 : 0.f; }
;             s0[r] = p0; s1[r] = p1; rsa[r & 3] += p0 + p1; }
;         lrun += (rsa[0] + rsa[1]) + (rsa[2] + rsa[3]);
; #pragma unroll
;         for (int s = 0; s < 2; ++s) {
;             v4u x; x.x = cvtpk(s0[8 * s + 0], s0[8 * s + 1]); x.y = cvtpk(s0[8 * s + 2], s0[8 * s + 3]); x.z = cvtpk(s0[8 * s + 4], s0[8 * s + 5]); x.w = cvtpk(s0[8 * s + 6], s0[8 * s + 7]); pb[0][s] = __builtin_bit_cast(bf16x8, x);
;             v4u y; y.x = cvtpk(s1[8 * s + 0], s1[8 * s + 1]); y.y = cvtpk(s1[8 * s + 2], s1[8 * s + 3]); y.z = cvtpk(s1[8 * s + 4], s1[8 * s + 5]); y.w = cvtpk(s1[8 * s + 6], s1[8 * s + 7]); pb[1][s] = __builtin_bit_cast(bf16x8, y); }
;     ...
;             if (wka) { vb = sa + KBUF + vlane; ATT_VREAD(vpre, 0); SM(wa0, wa1, a0, a1, pba);
;                 ATT_VREAD(va, 1); __builtin_amdgcn_s_setprio(1); ATT_PV(vpre, pba, 0); __builtin_amdgcn_s_setprio(0);
.LBB0_2113:
	v_sub_f32_e32 v96, v220, v206
	v_sub_f32_e32 v97, v231, v206
	v_exp_f32_e32 v96, v96
	v_exp_f32_e32 v97, v97
	v_sub_f32_e32 v107, v218, v206
	v_sub_f32_e32 v108, v230, v206
	v_sub_f32_e32 v220, v221, v206
	v_sub_f32_e32 v221, v227, v206
	v_exp_f32_e32 v107, v107
	v_exp_f32_e32 v108, v108
	v_sub_f32_e32 v110, v222, v206
	v_sub_f32_e32 v111, v229, v206
	v_exp_f32_e32 v220, v220
	v_exp_f32_e32 v221, v221
	v_sub_f32_e32 v215, v215, v206
	v_sub_f32_e32 v226, v226, v206
	v_exp_f32_e32 v110, v110
	v_exp_f32_e32 v111, v111
	v_sub_f32_e32 v113, v217, v206
	v_sub_f32_e32 v217, v228, v206
	v_exp_f32_e32 v215, v215
	v_exp_f32_e32 v226, v226
	v_sub_f32_e32 v219, v219, v206
	v_sub_f32_e32 v225, v225, v206
	v_exp_f32_e32 v113, v113
	v_exp_f32_e32 v217, v217
	v_exp_f32_e32 v219, v219
	v_exp_f32_e32 v225, v225
	v_sub_f32_e32 v216, v216, v206
	v_sub_f32_e32 v223, v223, v206
	v_cndmask_b32_e64 v96, v96, 0, s[20:21]
	v_cndmask_b32_e64 v97, v97, 0, s[68:69]
	v_exp_f32_e32 v216, v216
	v_exp_f32_e32 v223, v223
	v_add_f32_e32 v109, v96, v97
	v_cndmask_b32_e64 v107, v107, 0, s[10:11]
	v_cndmask_b32_e64 v108, v108, 0, s[66:67]
	v_cndmask_b32_e64 v220, v220, 0, s[16:17]
	v_cndmask_b32_e64 v221, v221, 0, s[60:61]
	v_sub_f32_e32 v90, v90, v206
	v_add_f32_e32 v109, 0, v109
	v_add_f32_e32 v112, v107, v108
	v_cndmask_b32_e64 v110, v110, 0, s[18:19]
	v_cndmask_b32_e64 v111, v111, 0, s[64:65]
	v_add_f32_e32 v227, v220, v221
	v_cndmask_b32_e64 v215, v215, 0, s[4:5]
	v_cndmask_b32_e64 v226, v226, 0, s[58:59]
	v_exp_f32_e32 v90, v90
	v_add_f32_e32 v112, 0, v112
	v_add_f32_e32 v218, v110, v111
	v_cndmask_b32_e64 v113, v113, 0, s[8:9]
	v_cndmask_b32_e64 v217, v217, 0, s[62:63]
	v_add_f32_e32 v109, v227, v109
	v_add_f32_e32 v227, v215, v226
	v_cndmask_b32_e64 v219, v219, 0, s[14:15]
	v_cndmask_b32_e64 v225, v225, 0, s[56:57]
	v_add_f32_e32 v218, 0, v218
	v_add_f32_e32 v222, v113, v217
	v_add_f32_e32 v112, v227, v112
	v_add_f32_e32 v227, v219, v225
	v_cndmask_b32_e64 v216, v216, 0, s[6:7]
	v_cndmask_b32_e64 v223, v223, 0, s[54:55]
	v_sub_f32_e32 v224, v224, v206
	v_add_f32_e32 v222, 0, v222
	v_add_f32_e32 v218, v227, v218
	v_exp_f32_e32 v224, v224
	v_add_f32_e32 v227, v216, v223
	v_add_f32_e32 v222, v227, v222
	v_cndmask_b32_e64 v227, v90, 0, s[12:13]
	v_sub_f32_e32 v90, v105, v206
	v_exp_f32_e32 v90, v90
	v_cndmask_b32_e64 v224, v224, 0, s[44:45]
	v_sub_f32_e32 v105, v106, v206
	v_add_f32_e32 v106, v227, v224
	v_add_f32_e32 v106, v106, v109
	v_cndmask_b32_e64 v109, v90, 0, s[50:51]
	v_sub_f32_e32 v90, v103, v206
	v_exp_f32_e32 v105, v105
	v_exp_f32_e32 v90, v90
	v_sub_f32_e32 v103, v104, v206
	v_exp_f32_e32 v103, v103
	v_cndmask_b32_e64 v228, v105, 0, s[52:53]
	v_cndmask_b32_e64 v105, v90, 0, s[46:47]
	v_sub_f32_e32 v90, v101, v206
	v_exp_f32_e32 v90, v90
	v_cndmask_b32_e64 v229, v103, 0, s[48:49]
	v_sub_f32_e32 v101, v102, v206
	v_exp_f32_e32 v101, v101
	v_cndmask_b32_e64 v103, v90, 0, s[40:41]
	v_sub_f32_e32 v90, v99, v206
	v_exp_f32_e32 v90, v90
	v_sub_f32_e32 v99, v100, v206
	v_exp_f32_e32 v99, v99
	v_cndmask_b32_e64 v230, v101, 0, s[42:43]
	v_cndmask_b32_e64 v101, v90, 0, s[36:37]
	v_sub_f32_e32 v90, v95, v206
	v_exp_f32_e32 v90, v90
	v_add_f32_e32 v100, v103, v230
	v_add_f32_e32 v100, v100, v222
	v_cndmask_b32_e64 v222, v99, 0, s[38:39]
	v_sub_f32_e32 v95, v98, v206
	v_exp_f32_e32 v95, v95
	v_add_f32_e32 v98, v101, v222
	v_add_f32_e32 v98, v98, v106
	v_cndmask_b32_e64 v106, v90, 0, s[30:31]
	v_sub_f32_e32 v90, v93, v206
	v_exp_f32_e32 v90, v90
	v_add_f32_e32 v104, v109, v228
	v_cndmask_b32_e64 v231, v95, 0, s[34:35]
	v_sub_f32_e32 v93, v94, v206
	v_add_f32_e32 v104, v104, v112
	v_exp_f32_e32 v93, v93
	v_add_f32_e32 v94, v106, v231
	v_add_f32_e32 v94, v94, v104
	v_cndmask_b32_e64 v104, v90, 0, s[26:27]
	v_sub_f32_e32 v90, v91, v206
	v_sub_f32_e32 v91, v92, v206
	v_exp_f32_e32 v90, v90
	v_exp_f32_e32 v91, v91
	v_add_f32_e32 v102, v105, v229
	v_cndmask_b32_e64 v232, v93, 0, s[28:29]
	v_add_f32_e32 v102, v102, v218
	v_add_f32_e32 v92, v104, v232
	v_add_f32_e32 v92, v92, v102
	v_cndmask_b32_e64 v102, v90, 0, s[22:23]
	v_cndmask_b32_e64 v233, v91, 0, s[24:25]
	v_add_f32_e32 v90, v102, v233
	v_add_f32_e32 v90, v90, v100
	v_add_f32_e32 v91, v98, v94
	v_add_f32_e32 v90, v92, v90
	v_add_f32_e32 v234, v91, v90
	v_cvt_pk_bf16_f32 v90, v96, v107
	v_cvt_pk_bf16_f32 v91, v110, v113
	v_cvt_pk_bf16_f32 v93, v219, v216
	v_cvt_pk_bf16_f32 v94, v97, v108
	v_cvt_pk_bf16_f32 v95, v111, v217
	v_cvt_pk_bf16_f32 v98, v227, v109
	v_cvt_pk_bf16_f32 v99, v105, v103
	v_cvt_pk_bf16_f32 v100, v101, v106
	v_cvt_pk_bf16_f32 v101, v104, v102
	ds_read_b64_tr_b16 v[102:103], v155 offset:20480
	ds_read_b64_tr_b16 v[104:105], v199 offset:22528
	ds_read_b64_tr_b16 v[106:107], v200 offset:20480
	ds_read_b64_tr_b16 v[108:109], v201 offset:22528
	ds_read_b64_tr_b16 v[110:111], v202 offset:20480
	ds_read_b64_tr_b16 v[112:113], v203 offset:22528
	ds_read_b64_tr_b16 v[216:217], v204 offset:20480
	ds_read_b64_tr_b16 v[218:219], v205 offset:22528
	v_cvt_pk_bf16_f32 v92, v220, v215
	v_cvt_pk_bf16_f32 v96, v221, v226
	v_cvt_pk_bf16_f32 v97, v225, v223
	v_cvt_pk_bf16_f32 v220, v224, v228
	v_cvt_pk_bf16_f32 v221, v229, v230
	v_cvt_pk_bf16_f32 v222, v222, v231
	v_cvt_pk_bf16_f32 v223, v232, v233
	s_setprio 1
	s_waitcnt lgkmcnt(12)
	v_mfma_f32_32x32x16_bf16 v[66:81], v[138:141], v[90:93], v[66:81]
	v_add_f32_e32 v192, v192, v234
	v_mfma_f32_32x32x16_bf16 v[50:65], v[134:137], v[90:93], v[50:65]
	s_waitcnt lgkmcnt(10)
	v_mfma_f32_32x32x16_bf16 v[34:49], v[86:89], v[90:93], v[34:49]
	s_waitcnt lgkmcnt(8)
; #define LAS __attribute__((address_space(3)))
; __device__ __forceinline__ int crow(int r, int hi) { return (r & 3) + 8 * (r >> 2) + 4 * hi; }
; #define ATT_VREAD(dst, q_) do { const LAS char* vp_ = (const LAS char*)vb + (((q_) >> 1) * 32 + 16 * ((q_) & 1)) * VSTR; \
;         _Pragma("unroll") for (int d_ = 0; d_ < 4; ++d_) { dst[d_][0] = vtr(vp_ + voff[d_][0]); dst[d_][1] = vtr(vp_ + 8 * VSTR + voff[d_][1]); } } while (0)
;     ...
;     auto QK = [&](const LAS unsigned char* sbase, f32x16& s0, f32x16& s1) {
;         const LAS unsigned char* kb = sbase + r32 * KSTR; const int kc0 = (koff >> 3) + hi;
; #pragma unroll
;         for (int r = 0; r < 16; ++r) { s0[r] = 0.f; s1[r] = 0.f; }
; #pragma unroll
;         for (int kh = 0; kh < NKS; kh += 4) {
;             bf16x8 ka[4][2];
; #pragma unroll
;             for (int ks = 0; ks < 4; ++ks) { const int ko = ((kc0 + 2 * (kh + ks)) ^ ksw) << 4; ka[ks][0] = *(const LAS bf16x8*)(kb + ko); ka[ks][1] = *(const LAS bf16x8*)(kb + 32 * KSTR + ko); }
;             __builtin_amdgcn_s_setprio(1);
; #pragma unroll
;             for (int ks = 0; ks < 4; ++ks) { s0 = __builtin_amdgcn_mfma_f32_32x32x16_bf16(ka[ks][0], qf[kh + ks], s0, 0, 0, 0); s1 = __builtin_amdgcn_mfma_f32_32x32x16_bf16(ka[ks][1], qf[kh + ks], s1, 0, 0, 0); }
;             __builtin_amdgcn_s_setprio(0);
;         }
;     };
;     auto SM = [&](unsigned w0, unsigned w1, f32x16& s0, f32x16& s1, bf16x8 (&pb)[2][2]) {
;         if (LAYER == 1) {
; #pragma unroll
;             for (int r = 0; r < 16; ++r) { const int kv = crow(r, hi); if (!((w0 >> kv) & 1u)) s0[r] = -1e30f; if (!((w1 >> kv) & 1u)) s1[r] = -1e30f; } }
;     ...
;             if (wka) { vb = sa + KBUF + vlane; ATT_VREAD(vpre, 0); SM(wa0, wa1, a0, a1, pba);
;                 ATT_VREAD(va, 1); __builtin_amdgcn_s_setprio(1); ATT_PV(vpre, pba, 0); __builtin_amdgcn_s_setprio(0);
;                 ATT_VREAD(vbb, 2); __builtin_amdgcn_s_setprio(1); ATT_PV(va, pba, 1); __builtin_amdgcn_s_setprio(0);
;                 ATT_VREAD(va, 3); __builtin_amdgcn_s_setprio(1); ATT_PV(vbb, pba, 2); __builtin_amdgcn_s_setprio(0);
;                 __builtin_amdgcn_s_setprio(1); ATT_PV(va, pba, 3); __builtin_amdgcn_s_setprio(0); }
;             if (LAYER == 1) { if (wkb) QK(sbb, b0, b1); }
	v_mfma_f32_32x32x16_bf16 v[18:33], v[82:85], v[90:93], v[18:33]
	s_setprio 0
	ds_read_b64_tr_b16 v[82:83], v155 offset:24576
	ds_read_b64_tr_b16 v[84:85], v199 offset:26624
	ds_read_b64_tr_b16 v[86:87], v200 offset:24576
	ds_read_b64_tr_b16 v[88:89], v201 offset:26624
	ds_read_b64_tr_b16 v[90:91], v202 offset:24576
	ds_read_b64_tr_b16 v[92:93], v203 offset:26624
	ds_read_b64_tr_b16 v[134:135], v204 offset:24576
	ds_read_b64_tr_b16 v[136:137], v205 offset:26624
	s_setprio 1
	s_waitcnt lgkmcnt(14)
	v_mfma_f32_32x32x16_bf16 v[66:81], v[102:105], v[98:101], v[66:81]
	s_waitcnt lgkmcnt(12)
	v_mfma_f32_32x32x16_bf16 v[50:65], v[106:109], v[98:101], v[50:65]
	s_waitcnt lgkmcnt(10)
	v_mfma_f32_32x32x16_bf16 v[34:49], v[110:113], v[98:101], v[34:49]
	s_waitcnt lgkmcnt(8)
	v_mfma_f32_32x32x16_bf16 v[18:33], v[216:219], v[98:101], v[18:33]
	s_setprio 0
	ds_read_b64_tr_b16 v[98:99], v155 offset:28672
	ds_read_b64_tr_b16 v[100:101], v199 offset:30720
	ds_read_b64_tr_b16 v[102:103], v200 offset:28672
	ds_read_b64_tr_b16 v[104:105], v201 offset:30720
	ds_read_b64_tr_b16 v[106:107], v202 offset:28672
	ds_read_b64_tr_b16 v[108:109], v203 offset:30720
	ds_read_b64_tr_b16 v[110:111], v204 offset:28672
	ds_read_b64_tr_b16 v[112:113], v205 offset:30720
	s_setprio 1
	s_waitcnt lgkmcnt(14)
	v_mfma_f32_32x32x16_bf16 v[66:81], v[82:85], v[94:97], v[66:81]
	s_waitcnt lgkmcnt(12)
	v_mfma_f32_32x32x16_bf16 v[50:65], v[86:89], v[94:97], v[50:65]
	s_waitcnt lgkmcnt(10)
	v_mfma_f32_32x32x16_bf16 v[34:49], v[90:93], v[94:97], v[34:49]
	s_waitcnt lgkmcnt(8)
	v_mfma_f32_32x32x16_bf16 v[18:33], v[134:137], v[94:97], v[18:33]
	s_setprio 0
	s_setprio 1
	s_waitcnt lgkmcnt(6)
	v_mfma_f32_32x32x16_bf16 v[66:81], v[98:101], v[220:223], v[66:81]
	s_waitcnt lgkmcnt(4)
	v_mfma_f32_32x32x16_bf16 v[50:65], v[102:105], v[220:223], v[50:65]
	s_waitcnt lgkmcnt(2)
	v_mfma_f32_32x32x16_bf16 v[34:49], v[106:109], v[220:223], v[34:49]
	s_waitcnt lgkmcnt(0)
	v_mfma_f32_32x32x16_bf16 v[18:33], v[110:113], v[220:223], v[18:33]
	s_setprio 0
.LBB0_2114:
	s_cmp_ge_i32 s85, s90
	s_cbranch_scc1 .LBB0_2118
	ds_read_b128 v[82:85], v214 offset:32768
	ds_read_b128 v[98:101], v214 offset:40960
	ds_read_b128 v[102:105], v213 offset:32768
	ds_read_b128 v[134:137], v213 offset:40960
	ds_read_b128 v[106:109], v212 offset:32768
	ds_read_b128 v[138:141], v212 offset:40960
	ds_read_b128 v[110:113], v211 offset:32768
	ds_read_b128 v[214:217], v211 offset:40960
	s_setprio 1
	s_waitcnt lgkmcnt(0)
	v_mfma_f32_32x32x16_bf16 v[82:97], v[82:85], v[4:7], 0
	v_mfma_f32_32x32x16_bf16 v[82:97], v[102:105], v[8:11], v[82:97]
	v_mfma_f32_32x32x16_bf16 v[82:97], v[106:109], v[12:15], v[82:97]
	v_mfma_f32_32x32x16_bf16 v[82:97], v[110:113], v[114:117], v[82:97]
	s_setprio 0
	ds_read_b128 v[102:105], v210 offset:32768
	ds_read_b128 v[218:221], v210 offset:40960
	ds_read_b128 v[106:109], v209 offset:32768
	ds_read_b128 v[222:225], v209 offset:40960
	ds_read_b128 v[110:113], v208 offset:32768
	ds_read_b128 v[226:229], v208 offset:40960
	ds_read_b128 v[208:211], v207 offset:32768
	ds_read_b128 v[230:233], v207 offset:40960
	s_setprio 1
	s_waitcnt lgkmcnt(0)
	v_mfma_f32_32x32x16_bf16 v[82:97], v[102:105], v[118:121], v[82:97]
	v_mfma_f32_32x32x16_bf16 v[82:97], v[106:109], v[122:125], v[82:97]
	v_mfma_f32_32x32x16_bf16 v[82:97], v[110:113], v[126:129], v[82:97]
	v_mfma_f32_32x32x16_bf16 v[82:97], v[208:211], v[130:133], v[82:97]
	s_setprio 0
	v_mfma_f32_32x32x16_bf16 v[98:113], v[98:101], v[4:7], 0
	v_and_b32_e32 v207, v156, v182
	v_cmp_eq_u32_e64 s[20:21], 0, v207
	v_and_b32_e32 v208, v156, v183
	v_cmp_eq_u32_e64 s[10:11], 0, v208
	s_nop 5
	v_cndmask_b32_e64 v212, v82, v158, s[20:21]
	v_and_b32_e32 v82, v157, v183
	v_cmp_eq_u32_e64 s[66:67], 0, v82
	v_mfma_f32_32x32x16_bf16 v[98:113], v[134:137], v[8:11], v[98:113]
	v_and_b32_e32 v82, v156, v191
	v_cmp_eq_u32_e64 s[50:51], 0, v82
	v_and_b32_e32 v82, v157, v191
	v_cmp_eq_u32_e64 s[52:53], 0, v82
	v_and_b32_e32 v82, v156, v193
	v_cmp_eq_u32_e64 s[46:47], 0, v82
	v_and_b32_e32 v82, v157, v193
	v_mfma_f32_32x32x16_bf16 v[98:113], v[138:141], v[12:15], v[98:113]
	v_cmp_eq_u32_e64 s[48:49], 0, v82
	v_and_b32_e32 v82, v156, v194
	v_cmp_eq_u32_e64 s[40:41], 0, v82
	v_and_b32_e32 v82, v157, v194
	v_cmp_eq_u32_e64 s[42:43], 0, v82
	v_and_b32_e32 v82, v156, v195
	v_cmp_eq_u32_e64 s[36:37], 0, v82
	v_mfma_f32_32x32x16_bf16 v[98:113], v[214:217], v[114:117], v[98:113]
	v_and_b32_e32 v82, v157, v195
	v_cmp_eq_u32_e64 s[38:39], 0, v82
	v_and_b32_e32 v82, v156, v196
	v_cmp_eq_u32_e64 s[30:31], 0, v82
	v_and_b32_e32 v82, v157, v196
	v_cmp_eq_u32_e64 s[34:35], 0, v82
	v_and_b32_e32 v82, v156, v197
	v_mfma_f32_32x32x16_bf16 v[98:113], v[218:221], v[118:121], v[98:113]
	v_cndmask_b32_e64 v210, v83, v158, s[10:11]
	v_and_b32_e32 v83, v156, v184
	v_cmp_eq_u32_e64 s[26:27], 0, v82
	v_and_b32_e32 v82, v157, v197
	v_and_b32_e32 v215, v157, v184
	v_cmp_eq_u32_e64 s[18:19], 0, v83
	v_cmp_eq_u32_e64 s[28:29], 0, v82
	v_mfma_f32_32x32x16_bf16 v[98:113], v[222:225], v[122:125], v[98:113]
	v_and_b32_e32 v82, v156, v198
	v_and_b32_e32 v207, v156, v185
	v_cndmask_b32_e64 v214, v84, v158, s[18:19]
	v_and_b32_e32 v83, v157, v185
	v_and_b32_e32 v84, v156, v186
	v_cmp_eq_u32_e64 s[64:65], 0, v215
	v_cmp_eq_u32_e64 s[22:23], 0, v82
	v_mfma_f32_32x32x16_bf16 v[98:113], v[226:229], v[126:129], v[98:113]
	v_and_b32_e32 v82, v157, v198
	v_and_b32_e32 v234, v157, v182
	v_cmp_eq_u32_e64 s[8:9], 0, v207
	v_cmp_eq_u32_e64 s[16:17], 0, v84
	v_and_b32_e32 v84, v157, v187
	v_cmp_eq_u32_e64 s[62:63], 0, v83
	v_cmp_eq_u32_e64 s[24:25], 0, v82
	v_mfma_f32_32x32x16_bf16 v[98:113], v[230:233], v[130:133], v[98:113]
; __device__ __forceinline__ int crow(int r, int hi) { return (r & 3) + 8 * (r >> 2) + 4 * hi; }
; #define ATT_VREAD(dst, q_) do { const LAS char* vp_ = (const LAS char*)vb + (((q_) >> 1) * 32 + 16 * ((q_) & 1)) * VSTR; \
;         _Pragma("unroll") for (int d_ = 0; d_ < 4; ++d_) { dst[d_][0] = vtr(vp_ + voff[d_][0]); dst[d_][1] = vtr(vp_ + 8 * VSTR + voff[d_][1]); } } while (0)
;     ...
;         if (LAYER == 1) {
; #pragma unroll
;             for (int r = 0; r < 16; ++r) { const int kv = crow(r, hi); if (!((w0 >> kv) & 1u)) s0[r] = -1e30f; if (!((w1 >> kv) & 1u)) s1[r] = -1e30f; } }
;         float mx = fmaxf(s0[0], s1[0]);
; #pragma unroll
;         for (int r = 1; r < 16; ++r) mx = fmaxf(mx, fmaxf(s0[r], s1[r]));
;         mx = fmaxf(mx, __shfl_xor(mx, 32));
;         const bool need = mx > mrun + 8.f;
;         if (__any(need)) { const float mnew = need ? mx : mrun, alpha = __builtin_amdgcn_exp2f(mrun - mnew); mrun = mnew; lrun *= alpha;
; #pragma unroll
;             for (int d = 0; d < 4; ++d)
; #pragma unroll
;                 for (int r = 0; r < 16; ++r) o[d][r] *= alpha; }
;     ...
;             if (wkb) { vb = sbb + KBUF + vlane; ATT_VREAD(vpre, 0); SM(wb0, wb1, b0, b1, pbb);
	v_max_f32_e32 v83, v210, v210
	v_cndmask_b32_e64 v209, v85, v158, s[8:9]
	v_and_b32_e32 v85, v157, v186
	v_cmp_eq_u32_e64 s[68:69], 0, v234
	v_cmp_eq_u32_e64 s[58:59], 0, v84
	v_max_f32_e32 v84, v214, v214
	v_and_b32_e32 v207, v156, v187
	s_nop 4
	v_cndmask_b32_e64 v222, v99, v158, s[66:67]
	v_cndmask_b32_e64 v221, v100, v158, s[64:65]
	v_max_f32_e32 v82, v222, v222
	v_cndmask_b32_e64 v220, v101, v158, s[62:63]
	v_max_f32_e32 v82, v83, v82
	v_max_f32_e32 v83, v221, v221
	v_cndmask_b32_e64 v223, v98, v158, s[68:69]
	v_cmp_eq_u32_e64 s[60:61], 0, v85
	v_max_f32_e32 v83, v84, v83
	v_max_f32_e32 v84, v220, v220
	v_max_f32_e32 v85, v209, v209
	v_cndmask_b32_e64 v213, v86, v158, s[16:17]
	v_cmp_eq_u32_e64 s[4:5], 0, v207
	v_cndmask_b32_e64 v219, v102, v158, s[60:61]
	v_max3_f32 v82, v212, v223, v82
	v_max_f32_e32 v84, v85, v84
	v_cndmask_b32_e64 v207, v87, v158, s[4:5]
	v_and_b32_e32 v86, v156, v188
	v_and_b32_e32 v87, v157, v188
	v_cndmask_b32_e64 v218, v103, v158, s[58:59]
	v_max3_f32 v82, v82, v83, v84
	v_max_f32_e32 v83, v219, v219
	v_max_f32_e32 v84, v213, v213
	v_and_b32_e32 v208, v156, v189
	v_cmp_eq_u32_e64 s[14:15], 0, v86
	v_and_b32_e32 v86, v157, v189
	v_cmp_eq_u32_e64 s[56:57], 0, v87
	v_max_f32_e32 v83, v84, v83
	v_max_f32_e32 v84, v218, v218
	v_max_f32_e32 v85, v207, v207
	v_cndmask_b32_e64 v211, v88, v158, s[14:15]
	v_cmp_eq_u32_e64 s[6:7], 0, v208
	v_cndmask_b32_e64 v217, v104, v158, s[56:57]
	v_cmp_eq_u32_e64 s[54:55], 0, v86
	v_max_f32_e32 v84, v85, v84
	v_cndmask_b32_e64 v208, v89, v158, s[6:7]
	v_and_b32_e32 v88, v156, v190
	v_and_b32_e32 v89, v157, v190
	v_cndmask_b32_e64 v215, v105, v158, s[54:55]
	v_max3_f32 v82, v82, v83, v84
	v_max_f32_e32 v83, v217, v217
	v_max_f32_e32 v84, v211, v211
	v_cmp_eq_u32_e64 s[12:13], 0, v88
	v_cmp_eq_u32_e64 s[44:45], 0, v89
	v_max_f32_e32 v83, v84, v83
	v_max_f32_e32 v84, v215, v215
	v_max_f32_e32 v85, v208, v208
	v_cndmask_b32_e64 v90, v90, v158, s[12:13]
	v_cndmask_b32_e64 v216, v106, v158, s[44:45]
	v_max_f32_e32 v84, v85, v84
	v_cndmask_b32_e64 v105, v91, v158, s[50:51]
	v_cndmask_b32_e64 v106, v107, v158, s[52:53]
	v_max3_f32 v82, v82, v83, v84
	v_max_f32_e32 v83, v216, v216
	v_max_f32_e32 v84, v90, v90
	v_max_f32_e32 v83, v84, v83
	v_max_f32_e32 v84, v106, v106
	v_max_f32_e32 v85, v105, v105
	v_cndmask_b32_e64 v103, v92, v158, s[46:47]
	v_cndmask_b32_e64 v104, v108, v158, s[48:49]
	v_max_f32_e32 v84, v85, v84
	v_cndmask_b32_e64 v101, v93, v158, s[40:41]
	v_cndmask_b32_e64 v102, v109, v158, s[42:43]
	v_max3_f32 v82, v82, v83, v84
	v_max_f32_e32 v83, v104, v104
	v_max_f32_e32 v84, v103, v103
	v_max_f32_e32 v83, v84, v83
	v_max_f32_e32 v84, v102, v102
	v_max_f32_e32 v85, v101, v101
	v_cndmask_b32_e64 v99, v94, v158, s[36:37]
	v_cndmask_b32_e64 v100, v110, v158, s[38:39]
	v_max_f32_e32 v84, v85, v84
	v_cndmask_b32_e64 v95, v95, v158, s[30:31]
	v_cndmask_b32_e64 v98, v111, v158, s[34:35]
	v_max3_f32 v82, v82, v83, v84
	v_max_f32_e32 v83, v100, v100
	v_max_f32_e32 v84, v99, v99
	v_max_f32_e32 v83, v84, v83
	v_max_f32_e32 v84, v98, v98
	v_max_f32_e32 v85, v95, v95
	v_cndmask_b32_e64 v93, v96, v158, s[26:27]
	v_cndmask_b32_e64 v94, v112, v158, s[28:29]
	v_max_f32_e32 v84, v85, v84
	v_cndmask_b32_e64 v91, v97, v158, s[22:23]
	v_cndmask_b32_e64 v92, v113, v158, s[24:25]
	v_max3_f32 v82, v82, v83, v84
	v_max_f32_e32 v83, v94, v94
	v_max_f32_e32 v84, v93, v93
	v_max_f32_e32 v83, v84, v83
	v_max_f32_e32 v84, v92, v92
	v_max_f32_e32 v85, v91, v91
	v_max_f32_e32 v84, v85, v84
	v_max3_f32 v96, v82, v83, v84
	s_waitcnt vmcnt(0)
	ds_read_b64_tr_b16 v[138:139], v155 offset:49152
	ds_read_b64_tr_b16 v[140:141], v199 offset:51200
	ds_read_b64_tr_b16 v[134:135], v200 offset:49152
	ds_read_b64_tr_b16 v[136:137], v201 offset:51200
	v_mov_b32_e32 v246, v96
	v_mov_b32_e32 v247, v96
	ds_read_b64_tr_b16 v[86:87], v202 offset:49152
	ds_read_b64_tr_b16 v[88:89], v203 offset:51200
	ds_read_b64_tr_b16 v[82:83], v204 offset:49152
	ds_read_b64_tr_b16 v[84:85], v205 offset:51200
	v_permlane32_swap_b32_e32 v246, v247
	v_max3_f32 v96, v96, v246, v247
	v_add_f32_e32 v97, 0x41000000, v206
	v_cmp_gt_f32_e32 vcc, v96, v97
	s_cbranch_vccz .LBB0_2117
	s_nop 0
	v_cndmask_b32_e32 v97, v206, v96, vcc
	v_sub_f32_e32 v96, v206, v97
	v_exp_f32_e32 v96, v96
	v_mov_b32_e32 v206, v97
	v_mul_f32_e32 v192, v192, v96
	v_pk_mul_f32 v[80:81], v[80:81], v[96:97] op_sel_hi:[1,0]
	v_pk_mul_f32 v[78:79], v[78:79], v[96:97] op_sel_hi:[1,0]
	v_pk_mul_f32 v[76:77], v[76:77], v[96:97] op_sel_hi:[1,0]
	v_pk_mul_f32 v[74:75], v[74:75], v[96:97] op_sel_hi:[1,0]
	v_pk_mul_f32 v[72:73], v[72:73], v[96:97] op_sel_hi:[1,0]
	v_pk_mul_f32 v[70:71], v[70:71], v[96:97] op_sel_hi:[1,0]
	v_pk_mul_f32 v[68:69], v[68:69], v[96:97] op_sel_hi:[1,0]
	v_pk_mul_f32 v[66:67], v[66:67], v[96:97] op_sel_hi:[1,0]
	v_pk_mul_f32 v[64:65], v[64:65], v[96:97] op_sel_hi:[1,0]
	v_pk_mul_f32 v[62:63], v[62:63], v[96:97] op_sel_hi:[1,0]
	v_pk_mul_f32 v[60:61], v[60:61], v[96:97] op_sel_hi:[1,0]
	v_pk_mul_f32 v[58:59], v[58:59], v[96:97] op_sel_hi:[1,0]
	v_pk_mul_f32 v[56:57], v[56:57], v[96:97] op_sel_hi:[1,0]
	v_pk_mul_f32 v[54:55], v[54:55], v[96:97] op_sel_hi:[1,0]
	v_pk_mul_f32 v[52:53], v[52:53], v[96:97] op_sel_hi:[1,0]
	v_pk_mul_f32 v[50:51], v[50:51], v[96:97] op_sel_hi:[1,0]
	v_pk_mul_f32 v[48:49], v[48:49], v[96:97] op_sel_hi:[1,0]
	v_pk_mul_f32 v[46:47], v[46:47], v[96:97] op_sel_hi:[1,0]
	v_pk_mul_f32 v[44:45], v[44:45], v[96:97] op_sel_hi:[1,0]
	v_pk_mul_f32 v[42:43], v[42:43], v[96:97] op_sel_hi:[1,0]
	v_pk_mul_f32 v[40:41], v[40:41], v[96:97] op_sel_hi:[1,0]
	v_pk_mul_f32 v[38:39], v[38:39], v[96:97] op_sel_hi:[1,0]
	v_pk_mul_f32 v[36:37], v[36:37], v[96:97] op_sel_hi:[1,0]
	v_pk_mul_f32 v[34:35], v[34:35], v[96:97] op_sel_hi:[1,0]
	v_pk_mul_f32 v[32:33], v[32:33], v[96:97] op_sel_hi:[1,0]
	v_pk_mul_f32 v[30:31], v[30:31], v[96:97] op_sel_hi:[1,0]
	v_pk_mul_f32 v[28:29], v[28:29], v[96:97] op_sel_hi:[1,0]
	v_pk_mul_f32 v[26:27], v[26:27], v[96:97] op_sel_hi:[1,0]
	v_pk_mul_f32 v[24:25], v[24:25], v[96:97] op_sel_hi:[1,0]
	v_pk_mul_f32 v[22:23], v[22:23], v[96:97] op_sel_hi:[1,0]
	v_pk_mul_f32 v[20:21], v[20:21], v[96:97] op_sel_hi:[1,0]
	v_pk_mul_f32 v[18:19], v[18:19], v[96:97] op_sel_hi:[1,0]
; __device__ __forceinline__ unsigned cvtpk(float lo, float hi) { typedef __bf16 b2 __attribute__((ext_vector_type(2))); f32x2 v = {lo, hi}; b2 b = __builtin_convertvector(v, b2); return __builtin_bit_cast(unsigned, b); }
; __device__ __forceinline__ int crow(int r, int hi) { return (r & 3) + 8 * (r >> 2) + 4 * hi; }
; #define ATT_VREAD(dst, q_) do { const LAS char* vp_ = (const LAS char*)vb + (((q_) >> 1) * 32 + 16 * ((q_) & 1)) * VSTR; \
;         _Pragma("unroll") for (int d_ = 0; d_ < 4; ++d_) { dst[d_][0] = vtr(vp_ + voff[d_][0]); dst[d_][1] = vtr(vp_ + 8 * VSTR + voff[d_][1]); } } while (0)
; #define ATT_PV(src, pb_, q_) do { _Pragma("unroll") for (int d_ = 0; d_ < 4; ++d_) { const s16x4 lo_ = src[d_][0], hh_ = src[d_][1]; \
;         const bf16x8 vf_ = (bf16x8){lo_[0], lo_[1], lo_[2], lo_[3], hh_[0], hh_[1], hh_[2], hh_[3]}; o[d_] = __builtin_amdgcn_mfma_f32_32x32x16_bf16(vf_, pb_[(q_) >> 1][(q_) & 1], o[d_], 0, 0, 0); } } while (0)
;     ...
;         float rsa[4] = {0.f, 0.f, 0.f, 0.f};
; #pragma unroll
;         for (int r = 0; r < 16; ++r) { float p0 = __builtin_amdgcn_exp2f(s0[r] - mrun), p1 = __builtin_amdgcn_exp2f(s1[r] - mrun);
;             if (LAYER == 1) { const int kv = crow(r, hi); p0 = ((w0 >> kv) & 1u) ? p0 : 0.f; p1 = ((w1 >> kv) & 1u) ? p1 : 0.f; }
;             s0[r] = p0; s1[r] = p1; rsa[r & 3] += p0 + p1; }
;         lrun += (rsa[0] + rsa[1]) + (rsa[2] + rsa[3]);
; #pragma unroll
;         for (int s = 0; s < 2; ++s) {
;             v4u x; x.x = cvtpk(s0[8 * s + 0], s0[8 * s + 1]); x.y = cvtpk(s0[8 * s + 2], s0[8 * s + 3]); x.z = cvtpk(s0[8 * s + 4], s0[8 * s + 5]); x.w = cvtpk(s0[8 * s + 6], s0[8 * s + 7]); pb[0][s] = __builtin_bit_cast(bf16x8, x);
;             v4u y; y.x = cvtpk(s1[8 * s + 0], s1[8 * s + 1]); y.y = cvtpk(s1[8 * s + 2], s1[8 * s + 3]); y.z = cvtpk(s1[8 * s + 4], s1[8 * s + 5]); y.w = cvtpk(s1[8 * s + 6], s1[8 * s + 7]); pb[1][s] = __builtin_bit_cast(bf16x8, y); }
;     ...
;             if (wkb) { vb = sbb + KBUF + vlane; ATT_VREAD(vpre, 0); SM(wb0, wb1, b0, b1, pbb);
;                 ATT_VREAD(va, 1); __builtin_amdgcn_s_setprio(1); ATT_PV(vpre, pbb, 0); __builtin_amdgcn_s_setprio(0);
.LBB0_2117:
	v_sub_f32_e32 v96, v212, v206
	v_sub_f32_e32 v97, v223, v206
	v_exp_f32_e32 v96, v96
	v_exp_f32_e32 v97, v97
	v_sub_f32_e32 v107, v210, v206
	v_sub_f32_e32 v113, v209, v206
	v_sub_f32_e32 v209, v213, v206
	v_sub_f32_e32 v210, v219, v206
	v_exp_f32_e32 v209, v209
	v_exp_f32_e32 v210, v210
	v_cndmask_b32_e64 v96, v96, 0, s[20:21]
	v_cndmask_b32_e64 v97, v97, 0, s[68:69]
	v_sub_f32_e32 v108, v222, v206
	v_add_f32_e32 v109, v96, v97
	v_cndmask_b32_e64 v209, v209, 0, s[16:17]
	v_cndmask_b32_e64 v210, v210, 0, s[60:61]
	v_exp_f32_e32 v107, v107
	v_exp_f32_e32 v108, v108
	v_add_f32_e32 v109, 0, v109
	v_sub_f32_e32 v110, v214, v206
	v_sub_f32_e32 v111, v221, v206
	v_sub_f32_e32 v207, v207, v206
	v_sub_f32_e32 v213, v218, v206
	v_add_f32_e32 v214, v209, v210
	v_exp_f32_e32 v110, v110
	v_exp_f32_e32 v111, v111
	v_sub_f32_e32 v156, v220, v206
	v_exp_f32_e32 v207, v207
	v_exp_f32_e32 v213, v213
	v_add_f32_e32 v109, v214, v109
	v_sub_f32_e32 v211, v211, v206
	v_sub_f32_e32 v214, v217, v206
	v_exp_f32_e32 v113, v113
	v_exp_f32_e32 v156, v156
	v_exp_f32_e32 v211, v211
	v_exp_f32_e32 v214, v214
	v_sub_f32_e32 v208, v208, v206
	v_sub_f32_e32 v215, v215, v206
	v_exp_f32_e32 v208, v208
	v_exp_f32_e32 v215, v215
	v_cndmask_b32_e64 v107, v107, 0, s[10:11]
	v_cndmask_b32_e64 v108, v108, 0, s[66:67]
	v_sub_f32_e32 v90, v90, v206
	v_add_f32_e32 v112, v107, v108
	v_cndmask_b32_e64 v110, v110, 0, s[18:19]
	v_cndmask_b32_e64 v111, v111, 0, s[64:65]
	v_cndmask_b32_e64 v207, v207, 0, s[4:5]
	v_cndmask_b32_e64 v213, v213, 0, s[58:59]
	v_exp_f32_e32 v90, v90
	v_add_f32_e32 v112, 0, v112
	v_add_f32_e32 v157, v110, v111
	v_cndmask_b32_e64 v113, v113, 0, s[8:9]
	v_cndmask_b32_e64 v156, v156, 0, s[62:63]
	v_add_f32_e32 v217, v207, v213
	v_cndmask_b32_e64 v211, v211, 0, s[14:15]
	v_cndmask_b32_e64 v214, v214, 0, s[56:57]
	v_add_f32_e32 v157, 0, v157
	v_add_f32_e32 v212, v113, v156
	v_add_f32_e32 v112, v217, v112
	v_add_f32_e32 v217, v211, v214
	v_cndmask_b32_e64 v208, v208, 0, s[6:7]
	v_cndmask_b32_e64 v215, v215, 0, s[54:55]
	v_sub_f32_e32 v216, v216, v206
	v_add_f32_e32 v212, 0, v212
	v_add_f32_e32 v157, v217, v157
	v_exp_f32_e32 v216, v216
	v_add_f32_e32 v217, v208, v215
	v_add_f32_e32 v212, v217, v212
	v_cndmask_b32_e64 v217, v90, 0, s[12:13]
	v_sub_f32_e32 v90, v105, v206
	v_exp_f32_e32 v90, v90
	v_cndmask_b32_e64 v216, v216, 0, s[44:45]
	v_sub_f32_e32 v105, v106, v206
	v_add_f32_e32 v106, v217, v216
	v_add_f32_e32 v106, v106, v109
	v_cndmask_b32_e64 v109, v90, 0, s[50:51]
	v_sub_f32_e32 v90, v103, v206
	v_exp_f32_e32 v105, v105
	v_exp_f32_e32 v90, v90
	v_sub_f32_e32 v103, v104, v206
	v_exp_f32_e32 v103, v103
	v_cndmask_b32_e64 v218, v105, 0, s[52:53]
	v_cndmask_b32_e64 v105, v90, 0, s[46:47]
	v_sub_f32_e32 v90, v101, v206
	v_exp_f32_e32 v90, v90
	v_cndmask_b32_e64 v219, v103, 0, s[48:49]
	v_sub_f32_e32 v101, v102, v206
	v_exp_f32_e32 v101, v101
	v_cndmask_b32_e64 v103, v90, 0, s[40:41]
	v_sub_f32_e32 v90, v99, v206
	v_exp_f32_e32 v90, v90
	v_sub_f32_e32 v99, v100, v206
	v_add_f32_e32 v102, v105, v219
	v_exp_f32_e32 v99, v99
	v_add_f32_e32 v102, v102, v157
	v_cndmask_b32_e64 v157, v101, 0, s[42:43]
	v_cndmask_b32_e64 v101, v90, 0, s[36:37]
	v_sub_f32_e32 v90, v95, v206
	v_exp_f32_e32 v90, v90
	v_cndmask_b32_e64 v220, v99, 0, s[38:39]
	v_sub_f32_e32 v95, v98, v206
	v_exp_f32_e32 v95, v95
	v_add_f32_e32 v98, v101, v220
	v_add_f32_e32 v98, v98, v106
	v_cndmask_b32_e64 v106, v90, 0, s[30:31]
	v_sub_f32_e32 v90, v93, v206
	v_exp_f32_e32 v90, v90
	v_add_f32_e32 v104, v109, v218
	v_cndmask_b32_e64 v221, v95, 0, s[34:35]
	v_sub_f32_e32 v93, v94, v206
	v_add_f32_e32 v104, v104, v112
	v_exp_f32_e32 v93, v93
	v_add_f32_e32 v94, v106, v221
	v_add_f32_e32 v94, v94, v104
	v_cndmask_b32_e64 v104, v90, 0, s[26:27]
	v_sub_f32_e32 v90, v91, v206
	v_sub_f32_e32 v91, v92, v206
	v_exp_f32_e32 v90, v90
	v_exp_f32_e32 v91, v91
	v_cndmask_b32_e64 v222, v93, 0, s[28:29]
	v_add_f32_e32 v92, v104, v222
	v_add_f32_e32 v100, v103, v157
	v_add_f32_e32 v92, v92, v102
	v_cndmask_b32_e64 v102, v90, 0, s[22:23]
	v_cndmask_b32_e64 v223, v91, 0, s[24:25]
	v_add_f32_e32 v100, v100, v212
	v_add_f32_e32 v90, v102, v223
	v_add_f32_e32 v90, v90, v100
	v_add_f32_e32 v91, v98, v94
	v_add_f32_e32 v90, v92, v90
	v_add_f32_e32 v224, v91, v90
	v_cvt_pk_bf16_f32 v90, v96, v107
	v_cvt_pk_bf16_f32 v91, v110, v113
	v_cvt_pk_bf16_f32 v92, v209, v207
	v_cvt_pk_bf16_f32 v93, v211, v208
	v_cvt_pk_bf16_f32 v94, v97, v108
	v_cvt_pk_bf16_f32 v95, v111, v156
	v_cvt_pk_bf16_f32 v96, v210, v213
	v_cvt_pk_bf16_f32 v98, v217, v109
	v_cvt_pk_bf16_f32 v99, v105, v103
	v_cvt_pk_bf16_f32 v100, v101, v106
	v_cvt_pk_bf16_f32 v101, v104, v102
	ds_read_b64_tr_b16 v[102:103], v155 offset:53248
	ds_read_b64_tr_b16 v[104:105], v199 offset:55296
	ds_read_b64_tr_b16 v[106:107], v200 offset:53248
	ds_read_b64_tr_b16 v[108:109], v201 offset:55296
	ds_read_b64_tr_b16 v[110:111], v202 offset:53248
	ds_read_b64_tr_b16 v[112:113], v203 offset:55296
	ds_read_b64_tr_b16 v[208:209], v204 offset:53248
	ds_read_b64_tr_b16 v[210:211], v205 offset:55296
	v_cvt_pk_bf16_f32 v97, v214, v215
	v_cvt_pk_bf16_f32 v212, v216, v218
	v_cvt_pk_bf16_f32 v213, v219, v157
	v_cvt_pk_bf16_f32 v214, v220, v221
	v_cvt_pk_bf16_f32 v215, v222, v223
	s_setprio 1
	s_waitcnt lgkmcnt(12)
; #define ATT_VREAD(dst, q_) do { const LAS char* vp_ = (const LAS char*)vb + (((q_) >> 1) * 32 + 16 * ((q_) & 1)) * VSTR; \
;         _Pragma("unroll") for (int d_ = 0; d_ < 4; ++d_) { dst[d_][0] = vtr(vp_ + voff[d_][0]); dst[d_][1] = vtr(vp_ + 8 * VSTR + voff[d_][1]); } } while (0)
; #define ATT_PV(src, pb_, q_) do { _Pragma("unroll") for (int d_ = 0; d_ < 4; ++d_) { const s16x4 lo_ = src[d_][0], hh_ = src[d_][1]; \
;         const bf16x8 vf_ = (bf16x8){lo_[0], lo_[1], lo_[2], lo_[3], hh_[0], hh_[1], hh_[2], hh_[3]}; o[d_] = __builtin_amdgcn_mfma_f32_32x32x16_bf16(vf_, pb_[(q_) >> 1][(q_) & 1], o[d_], 0, 0, 0); } } while (0)
;     ...
;             if (wkb) { vb = sbb + KBUF + vlane; ATT_VREAD(vpre, 0); SM(wb0, wb1, b0, b1, pbb);
;                 ATT_VREAD(va, 1); __builtin_amdgcn_s_setprio(1); ATT_PV(vpre, pbb, 0); __builtin_amdgcn_s_setprio(0);
;                 ATT_VREAD(vbb, 2); __builtin_amdgcn_s_setprio(1); ATT_PV(va, pbb, 1); __builtin_amdgcn_s_setprio(0);
;                 ATT_VREAD(va, 3); __builtin_amdgcn_s_setprio(1); ATT_PV(vbb, pbb, 2); __builtin_amdgcn_s_setprio(0);
;                 __builtin_amdgcn_s_setprio(1); ATT_PV(va, pbb, 3); __builtin_amdgcn_s_setprio(0); }
	v_mfma_f32_32x32x16_bf16 v[66:81], v[138:141], v[90:93], v[66:81]
	v_add_f32_e32 v192, v192, v224
	v_mfma_f32_32x32x16_bf16 v[50:65], v[134:137], v[90:93], v[50:65]
	s_waitcnt lgkmcnt(10)
	v_mfma_f32_32x32x16_bf16 v[34:49], v[86:89], v[90:93], v[34:49]
	s_waitcnt lgkmcnt(8)
	v_mfma_f32_32x32x16_bf16 v[18:33], v[82:85], v[90:93], v[18:33]
	s_setprio 0
	ds_read_b64_tr_b16 v[82:83], v155 offset:57344
	ds_read_b64_tr_b16 v[84:85], v199 offset:59392
	ds_read_b64_tr_b16 v[86:87], v200 offset:57344
	ds_read_b64_tr_b16 v[88:89], v201 offset:59392
	ds_read_b64_tr_b16 v[90:91], v202 offset:57344
	ds_read_b64_tr_b16 v[92:93], v203 offset:59392
	ds_read_b64_tr_b16 v[134:135], v204 offset:57344
	ds_read_b64_tr_b16 v[136:137], v205 offset:59392
	s_setprio 1
	s_waitcnt lgkmcnt(14)
	v_mfma_f32_32x32x16_bf16 v[66:81], v[102:105], v[98:101], v[66:81]
	s_waitcnt lgkmcnt(12)
	v_mfma_f32_32x32x16_bf16 v[50:65], v[106:109], v[98:101], v[50:65]
	s_waitcnt lgkmcnt(10)
	v_mfma_f32_32x32x16_bf16 v[34:49], v[110:113], v[98:101], v[34:49]
	s_waitcnt lgkmcnt(8)
	v_mfma_f32_32x32x16_bf16 v[18:33], v[208:211], v[98:101], v[18:33]
	s_setprio 0
	ds_read_b64_tr_b16 v[98:99], v155 offset:61440
	ds_read_b64_tr_b16 v[100:101], v199 offset:63488
	ds_read_b64_tr_b16 v[102:103], v200 offset:61440
	ds_read_b64_tr_b16 v[104:105], v201 offset:63488
	ds_read_b64_tr_b16 v[106:107], v202 offset:61440
	ds_read_b64_tr_b16 v[108:109], v203 offset:63488
	ds_read_b64_tr_b16 v[110:111], v204 offset:61440
	ds_read_b64_tr_b16 v[112:113], v205 offset:63488
	s_setprio 1
	s_waitcnt lgkmcnt(14)
	v_mfma_f32_32x32x16_bf16 v[66:81], v[82:85], v[94:97], v[66:81]
	s_waitcnt lgkmcnt(12)
	v_mfma_f32_32x32x16_bf16 v[50:65], v[86:89], v[94:97], v[50:65]
	s_waitcnt lgkmcnt(10)
	v_mfma_f32_32x32x16_bf16 v[34:49], v[90:93], v[94:97], v[34:49]
	s_waitcnt lgkmcnt(8)
	v_mfma_f32_32x32x16_bf16 v[18:33], v[134:137], v[94:97], v[18:33]
	s_setprio 0
	s_setprio 1
	s_waitcnt lgkmcnt(6)
	v_mfma_f32_32x32x16_bf16 v[66:81], v[98:101], v[212:215], v[66:81]
	s_waitcnt lgkmcnt(4)
	v_mfma_f32_32x32x16_bf16 v[50:65], v[102:105], v[212:215], v[50:65]
	s_waitcnt lgkmcnt(2)
	v_mfma_f32_32x32x16_bf16 v[34:49], v[106:109], v[212:215], v[34:49]
	s_waitcnt lgkmcnt(0)
	v_mfma_f32_32x32x16_bf16 v[18:33], v[110:113], v[212:215], v[18:33]
	s_setprio 0
